# phase 0 adaLN GEMV k-loop: the 16 weight-row loads of an unrolled iteration issued up front (hipcc serialised them through one register)
# speedup vs baseline: 1.0186x; 1.0171x over previous
.LBB0_74:
	v_lshl_add_u64 v[66:67], v[20:21], 0, s[6:7]
	global_load_dword v68, v[66:67], off
	s_mov_b32 s5, 0xc000
	v_add_co_u32_e32 v74, vcc, s40, v66
	s_nop 1
	v_addc_co_u32_e32 v75, vcc, 0, v67, vcc
	global_load_dword v76, v[74:75], off
	v_add_co_u32_e32 v80, vcc, s5, v66
	s_nop 1
	v_addc_co_u32_e32 v81, vcc, 0, v67, vcc
	global_load_dword v82, v[80:81], off
	s_mov_b32 s5, 0x12000
	v_add_co_u32_e32 v88, vcc, s5, v66
	s_nop 1
	v_addc_co_u32_e32 v89, vcc, 0, v67, vcc
	global_load_dword v90, v[88:89], off
	s_mov_b32 s5, 0x18000
	v_add_co_u32_e32 v94, vcc, s5, v66
	s_nop 1
	v_addc_co_u32_e32 v95, vcc, 0, v67, vcc
	global_load_dword v98, v[94:95], off
	s_mov_b32 s5, 0x1e000
	v_add_co_u32_e32 v102, vcc, s5, v66
	s_mov_b32 s5, 0x24000
	s_nop 0
	v_addc_co_u32_e32 v103, vcc, 0, v67, vcc
	v_add_co_u32_e32 v104, vcc, s5, v66
	global_load_dword v106, v[102:103], off
	s_nop 0
	v_addc_co_u32_e32 v105, vcc, 0, v67, vcc
	global_load_dword v102, v[104:105], off
	s_mov_b32 s5, 0x2a000
	v_add_co_u32_e32 v116, vcc, s5, v66
	s_nop 1
	v_addc_co_u32_e32 v117, vcc, 0, v67, vcc
	global_load_dword v80, v[116:117], off
	s_mov_b32 s5, 0x30000
	v_add_co_u32_e32 v118, vcc, s5, v66
	s_nop 1
	v_addc_co_u32_e32 v119, vcc, 0, v67, vcc
	global_load_dword v122, v[118:119], off
	s_mov_b32 s5, 0x36000
	v_add_co_u32_e32 v126, vcc, s5, v66
	s_mov_b32 s5, 0x3c000
	s_nop 0
	v_addc_co_u32_e32 v127, vcc, 0, v67, vcc
	v_add_co_u32_e32 v128, vcc, s5, v66
	global_load_dword v130, v[126:127], off
	s_nop 0
	v_addc_co_u32_e32 v129, vcc, 0, v67, vcc
	global_load_dword v126, v[128:129], off
	s_mov_b32 s5, 0x42000
	v_add_co_u32_e32 v140, vcc, s5, v66
	s_nop 1
	v_addc_co_u32_e32 v141, vcc, 0, v67, vcc
	global_load_dword v88, v[140:141], off
	s_mov_b32 s5, 0x48000
	v_add_co_u32_e32 v142, vcc, s5, v66
	s_nop 1
	v_addc_co_u32_e32 v143, vcc, 0, v67, vcc
	global_load_dword v146, v[142:143], off
	s_mov_b32 s5, 0x4e000
	v_add_co_u32_e32 v150, vcc, s5, v66
	s_mov_b32 s5, 0x54000
	s_nop 0
	v_addc_co_u32_e32 v151, vcc, 0, v67, vcc
	v_add_co_u32_e32 v152, vcc, s5, v66
	global_load_dword v104, v[150:151], off
	s_nop 0
	v_addc_co_u32_e32 v153, vcc, 0, v67, vcc
	global_load_dword v150, v[152:153], off
	s_mov_b32 s5, 0x5a000
	v_add_co_u32_e32 v162, vcc, s5, v66
	s_nop 1
	v_addc_co_u32_e32 v163, vcc, 0, v67, vcc
	global_load_dword v66, v[162:163], off
	ds_read_b128 v[42:45], v41
	ds_read_b128 v[10:13], v41 offset:16
	ds_read_b128 v[6:9], v41 offset:32
	ds_read_b128 v[2:5], v41 offset:48
	ds_read_b128 v[46:49], v41 offset:2048
	s_waitcnt lgkmcnt(4)
	v_mov_b32_e32 v50, v42
	s_add_u32 s6, s6, 0x60000
	s_addc_u32 s7, s7, 0
	s_waitcnt lgkmcnt(0)
	v_mov_b32_e32 v51, v46
	v_mov_b32_e32 v46, v43
	s_cmp_eq_u32 s6, 0x300000
	s_waitcnt vmcnt(15)
	v_mov_b32_e32 v70, v68
	v_mov_b32_e32 v71, v63
	v_pk_fma_f32 v[26:27], v[70:71], v[50:51], v[26:27] op_sel_hi:[0,1,1]
	ds_read_b128 v[50:53], v41 offset:4096
	ds_read_b128 v[54:57], v41 offset:6144
	ds_read_b128 v[58:61], v41 offset:8192
	s_waitcnt lgkmcnt(2)
	v_mov_b32_e32 v64, v50
	s_waitcnt lgkmcnt(1)
	v_fmac_f32_e32 v14, v68, v54
	s_waitcnt lgkmcnt(0)
	v_mov_b32_e32 v65, v58
	v_mov_b32_e32 v72, v68
	v_mov_b32_e32 v73, v63
	v_pk_fma_f32 v[24:25], v[72:73], v[64:65], v[24:25] op_sel_hi:[0,1,1]
	v_mov_b32_e32 v58, v51
	s_waitcnt vmcnt(14)
	v_mov_b32_e32 v74, v76
	v_mov_b32_e32 v75, v43
	v_pk_fma_f32 v[26:27], v[74:75], v[46:47], v[26:27] op_sel_hi:[0,1,1]
	v_fmac_f32_e32 v14, v76, v55
	v_mov_b32_e32 v78, v76
	v_mov_b32_e32 v79, v43
	v_pk_fma_f32 v[24:25], v[78:79], v[58:59], v[24:25] op_sel_hi:[0,1,1]
	v_mov_b32_e32 v46, v44
	v_mov_b32_e32 v47, v48
	v_mov_b32_e32 v48, v45
	s_waitcnt vmcnt(13)
	v_mov_b32_e32 v84, v82
	v_mov_b32_e32 v85, v81
	v_pk_fma_f32 v[26:27], v[84:85], v[46:47], v[26:27] op_sel_hi:[0,1,1]
	v_mov_b32_e32 v46, v52
	v_mov_b32_e32 v47, v60
	v_fmac_f32_e32 v14, v82, v56
	v_mov_b32_e32 v86, v82
	v_mov_b32_e32 v87, v81
	v_pk_fma_f32 v[24:25], v[86:87], v[46:47], v[24:25] op_sel_hi:[0,1,1]
	v_mov_b32_e32 v60, v53
	s_waitcnt vmcnt(12)
	v_mov_b32_e32 v92, v90
	v_mov_b32_e32 v93, v89
	v_pk_fma_f32 v[54:55], v[92:93], v[60:61], v[24:25] op_sel_hi:[0,1,1]
	v_mov_b32_e32 v96, v90
	v_mov_b32_e32 v97, v89
	v_pk_fma_f32 v[44:45], v[96:97], v[48:49], v[26:27] op_sel_hi:[0,1,1]
	ds_read_b128 v[24:27], v41 offset:2064
	v_fmac_f32_e32 v14, v90, v57
	v_mov_b32_e32 v42, v10
	s_waitcnt lgkmcnt(0)
	v_mov_b32_e32 v43, v24
	v_mov_b32_e32 v24, v11
	s_waitcnt vmcnt(11)
	v_mov_b32_e32 v94, v98
	v_mov_b32_e32 v95, v57
	v_pk_fma_f32 v[58:59], v[94:95], v[42:43], v[44:45] op_sel_hi:[0,1,1]
	ds_read_b128 v[42:45], v41 offset:4112
	ds_read_b128 v[46:49], v41 offset:6160
	ds_read_b128 v[50:53], v41 offset:8208
	s_waitcnt lgkmcnt(2)
	v_mov_b32_e32 v60, v42
	s_waitcnt lgkmcnt(1)
	v_fmac_f32_e32 v14, v98, v46
	s_waitcnt lgkmcnt(0)
	v_mov_b32_e32 v61, v50
	v_mov_b32_e32 v100, v98
	v_mov_b32_e32 v101, v57
	v_pk_fma_f32 v[54:55], v[100:101], v[60:61], v[54:55] op_sel_hi:[0,1,1]
	v_mov_b32_e32 v50, v43
	v_mov_b32_e32 v46, v12
	s_waitcnt vmcnt(10)
	v_mov_b32_e32 v108, v106
	v_mov_b32_e32 v109, v11
	v_pk_fma_f32 v[24:25], v[108:109], v[24:25], v[58:59] op_sel_hi:[0,1,1]
	v_fmac_f32_e32 v14, v106, v47
	v_mov_b32_e32 v47, v26
	v_mov_b32_e32 v110, v106
	v_mov_b32_e32 v111, v11
	v_pk_fma_f32 v[10:11], v[110:111], v[50:51], v[54:55] op_sel_hi:[0,1,1]
	s_waitcnt vmcnt(9)
	v_mov_b32_e32 v112, v102
	v_mov_b32_e32 v113, v105
	v_pk_fma_f32 v[24:25], v[112:113], v[46:47], v[24:25] op_sel_hi:[0,1,1]
	v_mov_b32_e32 v46, v44
	v_mov_b32_e32 v47, v52
	v_fmac_f32_e32 v14, v102, v48
	v_mov_b32_e32 v114, v102
	v_mov_b32_e32 v115, v105
	v_pk_fma_f32 v[10:11], v[114:115], v[46:47], v[10:11] op_sel_hi:[0,1,1]
	v_mov_b32_e32 v52, v45
	v_mov_b32_e32 v26, v13
	s_waitcnt vmcnt(8)
	v_mov_b32_e32 v116, v80
	v_mov_b32_e32 v117, v13
	v_pk_fma_f32 v[50:51], v[116:117], v[52:53], v[10:11] op_sel_hi:[0,1,1]
	v_mov_b32_e32 v120, v80
	v_mov_b32_e32 v121, v13
	v_pk_fma_f32 v[24:25], v[120:121], v[26:27], v[24:25] op_sel_hi:[0,1,1]
	v_fmac_f32_e32 v14, v80, v49
	ds_read_b128 v[10:13], v41 offset:2080
	v_mov_b32_e32 v26, v6
	s_waitcnt lgkmcnt(0)
	v_mov_b32_e32 v27, v10
	v_mov_b32_e32 v10, v7
	s_waitcnt vmcnt(7)
	v_mov_b32_e32 v118, v122
	v_mov_b32_e32 v119, v53
	v_pk_fma_f32 v[54:55], v[118:119], v[26:27], v[24:25] op_sel_hi:[0,1,1]
	ds_read_b128 v[24:27], v41 offset:4128
	ds_read_b128 v[42:45], v41 offset:6176
	ds_read_b128 v[46:49], v41 offset:8224
	s_waitcnt lgkmcnt(2)
	v_mov_b32_e32 v56, v24
	s_waitcnt lgkmcnt(1)
	v_fmac_f32_e32 v14, v122, v42
	s_waitcnt lgkmcnt(0)
	v_mov_b32_e32 v57, v46
	v_mov_b32_e32 v124, v122
	v_mov_b32_e32 v125, v53
	v_pk_fma_f32 v[50:51], v[124:125], v[56:57], v[50:51] op_sel_hi:[0,1,1]
	v_mov_b32_e32 v46, v25
	v_mov_b32_e32 v42, v8
	s_waitcnt vmcnt(6)
	v_mov_b32_e32 v132, v130
	v_mov_b32_e32 v133, v7
	v_pk_fma_f32 v[10:11], v[132:133], v[10:11], v[54:55] op_sel_hi:[0,1,1]
	v_fmac_f32_e32 v14, v130, v43
	v_mov_b32_e32 v43, v12
	v_mov_b32_e32 v134, v130
	v_mov_b32_e32 v135, v7
	v_pk_fma_f32 v[6:7], v[134:135], v[46:47], v[50:51] op_sel_hi:[0,1,1]
	s_waitcnt vmcnt(5)
	v_mov_b32_e32 v136, v126
	v_mov_b32_e32 v137, v129
	v_pk_fma_f32 v[10:11], v[136:137], v[42:43], v[10:11] op_sel_hi:[0,1,1]
	v_mov_b32_e32 v42, v26
	v_mov_b32_e32 v43, v48
	v_fmac_f32_e32 v14, v126, v44
	v_mov_b32_e32 v138, v126
	v_mov_b32_e32 v139, v129
	v_pk_fma_f32 v[6:7], v[138:139], v[42:43], v[6:7] op_sel_hi:[0,1,1]
	v_mov_b32_e32 v48, v27
	v_mov_b32_e32 v12, v9
	s_waitcnt vmcnt(4)
	v_mov_b32_e32 v140, v88
	v_mov_b32_e32 v141, v9
	v_pk_fma_f32 v[24:25], v[140:141], v[48:49], v[6:7] op_sel_hi:[0,1,1]
	v_mov_b32_e32 v144, v88
	v_mov_b32_e32 v145, v9
	v_pk_fma_f32 v[10:11], v[144:145], v[12:13], v[10:11] op_sel_hi:[0,1,1]
	v_fmac_f32_e32 v14, v88, v45
	ds_read_b128 v[6:9], v41 offset:2096
	v_mov_b32_e32 v12, v2
	s_waitcnt lgkmcnt(0)
	v_mov_b32_e32 v13, v6
	v_mov_b32_e32 v6, v3
	s_waitcnt vmcnt(3)
	v_mov_b32_e32 v142, v146
	v_mov_b32_e32 v143, v27
	v_pk_fma_f32 v[50:51], v[142:143], v[12:13], v[10:11] op_sel_hi:[0,1,1]
	ds_read_b128 v[10:13], v41 offset:4144
	ds_read_b128 v[42:45], v41 offset:6192
	ds_read_b128 v[46:49], v41 offset:8240
	v_add_u32_e32 v41, 64, v41
	s_waitcnt lgkmcnt(2)
	v_mov_b32_e32 v52, v10
	s_waitcnt lgkmcnt(1)
	v_fmac_f32_e32 v14, v146, v42
	s_waitcnt lgkmcnt(0)
	v_mov_b32_e32 v53, v46
	v_mov_b32_e32 v148, v146
	v_mov_b32_e32 v149, v27
	v_pk_fma_f32 v[24:25], v[148:149], v[52:53], v[24:25] op_sel_hi:[0,1,1]
	v_mov_b32_e32 v46, v11
	s_waitcnt vmcnt(2)
	v_mov_b32_e32 v154, v104
	v_mov_b32_e32 v155, v3
	v_pk_fma_f32 v[6:7], v[154:155], v[6:7], v[50:51] op_sel_hi:[0,1,1]
	v_fmac_f32_e32 v14, v104, v43
	v_mov_b32_e32 v156, v104
	v_mov_b32_e32 v157, v3
	v_pk_fma_f32 v[2:3], v[156:157], v[46:47], v[24:25] op_sel_hi:[0,1,1]
	v_mov_b32_e32 v24, v4
	v_mov_b32_e32 v25, v8
	s_waitcnt vmcnt(1)
	v_mov_b32_e32 v158, v150
	v_mov_b32_e32 v159, v153
	v_pk_fma_f32 v[6:7], v[158:159], v[24:25], v[6:7] op_sel_hi:[0,1,1]
	v_mov_b32_e32 v24, v12
	v_mov_b32_e32 v25, v48
	v_fmac_f32_e32 v14, v150, v44
	v_mov_b32_e32 v160, v150
	v_mov_b32_e32 v161, v153
	v_pk_fma_f32 v[2:3], v[160:161], v[24:25], v[2:3] op_sel_hi:[0,1,1]
	v_mov_b32_e32 v8, v5
	v_mov_b32_e32 v48, v13
	s_waitcnt vmcnt(0)
	v_mov_b32_e32 v162, v66
	v_mov_b32_e32 v163, v5
	v_pk_fma_f32 v[26:27], v[162:163], v[8:9], v[6:7] op_sel_hi:[0,1,1]
	v_fmac_f32_e32 v14, v66, v45
	v_mov_b32_e32 v164, v66
	v_mov_b32_e32 v165, v5
	v_pk_fma_f32 v[24:25], v[164:165], v[48:49], v[2:3] op_sel_hi:[0,1,1]
	s_cbranch_scc0 .LBB0_74
	s_movk_i32 s5, 0x500
	v_mul_lo_u32 v2, v40, s5
	v_lshl_or_b32 v2, v19, 2, v2
	v_cmp_gt_i32_e32 vcc, 64, v18
	ds_write2st64_b32 v2, v26, v27 offset0:40 offset1:41
	ds_write2st64_b32 v2, v24, v14 offset0:42 offset1:43
	ds_write_b32 v2, v25 offset:11264
	s_waitcnt lgkmcnt(0)
	s_barrier
	s_and_saveexec_b64 s[6:7], vcc
	s_cbranch_execz .LBB0_79
	s_cmp_lg_u32 s8, 0
	v_mov_b32_e32 v2, 0
	s_cbranch_scc1 .LBB0_78
	s_mul_i32 s5, s9, 0x1800
	s_add_i32 s5, s5, s4
	v_add_u32_e32 v2, s5, v18
	v_readlane_b32 s44, v241, 41
	v_ashrrev_i32_e32 v3, 31, v2
	v_readlane_b32 s46, v241, 43
	v_readlane_b32 s47, v241, 44
	v_readlane_b32 s45, v241, 42
	v_readlane_b32 s48, v241, 45
	v_lshl_add_u64 v[2:3], v[2:3], 2, s[46:47]
	global_load_dword v2, v[2:3], off
	v_readlane_b32 s49, v241, 46
	v_readlane_b32 s50, v241, 47
	v_readlane_b32 s51, v241, 48
	v_readlane_b32 s52, v241, 49
	v_readlane_b32 s53, v241, 50
	v_readlane_b32 s54, v241, 51
	v_readlane_b32 s55, v241, 52
	v_readlane_b32 s56, v241, 53
	v_readlane_b32 s57, v241, 54
	v_readlane_b32 s58, v241, 55
	v_readlane_b32 s59, v241, 56
